# P0 conversion blocks dealt as one list over gates|ffn1|mixer (mixer start shifted by 96): 9..10 items per workgroup instead of 9..11
# speedup vs baseline: 1.0149x; 1.0075x over previous
.Lc16_ffn1_done:
	v_readlane_b32 s48, v255, 27
	v_readlane_b32 s49, v255, 28
	v_mul_u32_u24_e32 v138, 0x28000, v136
	v_lshl_add_u32 v138, v137, 4, v138
	s_mul_i32 s3, s1, 0x1400000
	s_nop 1
	s_add_u32 s48, s48, s3
	s_addc_u32 s49, s49, 0
	s_mov_b32 s0, s72
	s_cmpk_lg_i32 s33, 0x100
	s_cbranch_scc1 .Lc16_mixer_start
	s_sub_i32 s0, s72, 96
	s_cmp_lt_i32 s0, 0
	s_cselect_b32 s3, 0x100, 0
	s_add_i32 s0, s0, s3
.Lc16_mixer_start:
	s_cmp_ge_u32 s0, 0x280
	s_cbranch_scc1 .Lc16_mixer_done
	s_lshl_b32 s3, s0, 6
	s_add_u32 s56, s48, s3
	s_addc_u32 s57, s49, 0
	global_load_dwordx4 v[6:9], v138, s[56:57]
	s_add_u32 s56, s56, 0xa000
	s_addc_u32 s57, s57, 0
	global_load_dwordx4 v[10:13], v138, s[56:57]
	s_add_u32 s56, s56, 0xa000
	s_addc_u32 s57, s57, 0
	global_load_dwordx4 v[14:17], v138, s[56:57]
	s_add_u32 s56, s56, 0xa000
	s_addc_u32 s57, s57, 0
	global_load_dwordx4 v[18:21], v138, s[56:57]
	s_add_u32 s56, s56, 0x262000
	s_addc_u32 s57, s57, 0
	global_load_dwordx4 v[22:25], v138, s[56:57]
	s_add_u32 s56, s56, 0xa000
	s_addc_u32 s57, s57, 0
	global_load_dwordx4 v[26:29], v138, s[56:57]
	s_add_u32 s56, s56, 0xa000
	s_addc_u32 s57, s57, 0
	global_load_dwordx4 v[30:33], v138, s[56:57]
	s_add_u32 s56, s56, 0xa000
	s_addc_u32 s57, s57, 0
	global_load_dwordx4 v[34:37], v138, s[56:57]
	s_add_u32 s56, s56, 0x262000
	s_addc_u32 s57, s57, 0
	global_load_dwordx4 v[38:41], v138, s[56:57]
	s_add_u32 s56, s56, 0xa000
	s_addc_u32 s57, s57, 0
	global_load_dwordx4 v[42:45], v138, s[56:57]
	s_add_u32 s56, s56, 0xa000
	s_addc_u32 s57, s57, 0
	global_load_dwordx4 v[46:49], v138, s[56:57]
	s_add_u32 s56, s56, 0xa000
	s_addc_u32 s57, s57, 0
	global_load_dwordx4 v[50:53], v138, s[56:57]
	s_add_u32 s56, s56, 0x262000
	s_addc_u32 s57, s57, 0
	global_load_dwordx4 v[54:57], v138, s[56:57]
	s_add_u32 s56, s56, 0xa000
	s_addc_u32 s57, s57, 0
	global_load_dwordx4 v[58:61], v138, s[56:57]
	s_add_u32 s56, s56, 0xa000
	s_addc_u32 s57, s57, 0
	global_load_dwordx4 v[62:65], v138, s[56:57]
	s_add_u32 s56, s56, 0xa000
	s_addc_u32 s57, s57, 0
	global_load_dwordx4 v[66:69], v138, s[56:57]
	s_add_u32 s56, s56, 0x262000
	s_addc_u32 s57, s57, 0
	global_load_dwordx4 v[70:73], v138, s[56:57]
	s_add_u32 s56, s56, 0xa000
	s_addc_u32 s57, s57, 0
	global_load_dwordx4 v[74:77], v138, s[56:57]
	s_add_u32 s56, s56, 0xa000
	s_addc_u32 s57, s57, 0
	global_load_dwordx4 v[78:81], v138, s[56:57]
	s_add_u32 s56, s56, 0xa000
	s_addc_u32 s57, s57, 0
	global_load_dwordx4 v[82:85], v138, s[56:57]
	s_add_u32 s56, s56, 0x262000
	s_addc_u32 s57, s57, 0
	global_load_dwordx4 v[86:89], v138, s[56:57]
	s_add_u32 s56, s56, 0xa000
	s_addc_u32 s57, s57, 0
	global_load_dwordx4 v[90:93], v138, s[56:57]
	s_add_u32 s56, s56, 0xa000
	s_addc_u32 s57, s57, 0
	global_load_dwordx4 v[94:97], v138, s[56:57]
	s_add_u32 s56, s56, 0xa000
	s_addc_u32 s57, s57, 0
	global_load_dwordx4 v[98:101], v138, s[56:57]
	s_add_u32 s56, s56, 0x262000
	s_addc_u32 s57, s57, 0
	global_load_dwordx4 v[102:105], v138, s[56:57]
	s_add_u32 s56, s56, 0xa000
	s_addc_u32 s57, s57, 0
	global_load_dwordx4 v[106:109], v138, s[56:57]
	s_add_u32 s56, s56, 0xa000
	s_addc_u32 s57, s57, 0
	global_load_dwordx4 v[110:113], v138, s[56:57]
	s_add_u32 s56, s56, 0xa000
	s_addc_u32 s57, s57, 0
	global_load_dwordx4 v[114:117], v138, s[56:57]
	s_add_u32 s56, s56, 0x262000
	s_addc_u32 s57, s57, 0
	global_load_dwordx4 v[118:121], v138, s[56:57]
	s_add_u32 s56, s56, 0xa000
	s_addc_u32 s57, s57, 0
	global_load_dwordx4 v[122:125], v138, s[56:57]
	s_add_u32 s56, s56, 0xa000
	s_addc_u32 s57, s57, 0
	global_load_dwordx4 v[126:129], v138, s[56:57]
	s_add_u32 s56, s56, 0xa000
	s_addc_u32 s57, s57, 0
	global_load_dwordx4 v[130:133], v138, s[56:57]
